# lru2 tile loop: z loads kept in flight past the conv wait, scan LDS reads issued up front, chunk-carry load issued before the scan
# baseline (speedup 1.0000x reference)
; __device__ __forceinline__ void unpack8(u32x4 w, float* f) { f[0] = bflo(w.x); f[1] = bfhi(w.x); f[2] = bflo(w.y); f[3] = bfhi(w.y); f[4] = bflo(w.z); f[5] = bfhi(w.z); f[6] = bflo(w.w); f[7] = bfhi(w.w); }
; template <int PASS> __device__ void lru_phase(const Params& p, unsigned char* smem) {
;     ...
;     for (int tile = blockIdx.x; tile < 4096; tile += gridDim.x) {
;         const int jb = tile & 15, c = (tile >> 4) & 63, b = tile >> 10;
;         const int row0 = b * SEQL + c * 64;
;         u16 zpre[16];
;         if (PASS == 2) {
; #pragma unroll
;             for (int tt = 0; tt < 16; ++tt) zpre[tt] = Y0[(size_t)(row0 + (tid >> 7) * 16 + tt) * 4096 + jb * 128 + (tid & 127)];
;         }
; #pragma unroll
;         for (int it = 0; it < 2; ++it) {
;             const int t = (tid >> 4) + 32 * it, c8 = (tid & 15) * 8, ch = jb * 128 + c8;
;             float acc[8];
;             { const f32x4 b0 = *(const f32x4*)(cb + ch), b1 = *(const f32x4*)(cb + ch + 4);
; #pragma unroll
;               for (int i = 0; i < 4; ++i) { acc[i] = b0[i]; acc[4 + i] = b1[i]; } }
; #pragma unroll
;             for (int j = 0; j < 4; ++j) { float xv[8]; unpack8(craw[it][j], xv);
;                 const f32x4 w0 = *(const f32x4*)(cw + j * 2048 + ch), w1 = *(const f32x4*)(cw + j * 2048 + ch + 4);
.LBB0_542:
	s_bfe_u32 s24, s37, 0x60004
	s_ashr_i32 s25, s37, 10
	s_lshl_b32 s4, s25, 12
	s_lshl_b32 s5, s24, 6
	s_or_b32 s38, s5, s4
	s_and_b32 s40, s37, 15
	v_add_u32_e32 v108, s38, v131
	s_lshl_b32 s12, s40, 8
	v_ashrrev_i32_e32 v109, 31, v108
	v_lshl_add_u64 v[110:111], v[124:125], 0, s[12:13]
	v_lshlrev_b64 v[68:69], 13, v[108:109]
	v_lshl_add_u64 v[112:113], v[110:111], 0, v[68:69]
	v_or_b32_e32 v68, 1, v108
	v_ashrrev_i32_e32 v69, 31, v68
	v_lshlrev_b64 v[68:69], 13, v[68:69]
	v_lshl_add_u64 v[114:115], v[110:111], 0, v[68:69]
	v_or_b32_e32 v68, 2, v108
	v_ashrrev_i32_e32 v69, 31, v68
	s_lshl_b32 s39, s40, 7
	v_lshlrev_b64 v[68:69], 13, v[68:69]
	v_readlane_b32 s44, v251, 0
	v_lshl_add_u64 v[116:117], v[110:111], 0, v[68:69]
	v_or_b32_e32 v68, 3, v108
	v_or_b32_e32 v66, s39, v134
	v_readlane_b32 s46, v251, 2
	v_readlane_b32 s47, v251, 3
	v_ashrrev_i32_e32 v69, 31, v68
	v_lshlrev_b32_e32 v66, 2, v66
	s_mov_b64 s[42:43], s[46:47]
	v_lshlrev_b64 v[68:69], 13, v[68:69]
	v_lshl_add_u64 v[104:105], s[42:43], 0, v[66:67]
	v_lshl_add_u64 v[118:119], v[110:111], 0, v[68:69]
	v_or_b32_e32 v68, 4, v108
	v_add_co_u32_e32 v76, vcc, s28, v104
	v_ashrrev_i32_e32 v69, 31, v68
	s_nop 0
	v_addc_co_u32_e32 v77, vcc, 0, v105, vcc
	v_lshlrev_b64 v[68:69], 13, v[68:69]
	v_readlane_b32 s48, v251, 4
	v_readlane_b32 s49, v251, 5
	v_add_co_u32_e32 v80, vcc, s29, v104
	v_lshl_add_u64 v[120:121], v[110:111], 0, v[68:69]
	s_nop 2
	global_load_dwordx4 v[68:71], v66, s[48:49]
	global_load_dwordx4 v[72:75], v66, s[46:47]
	v_addc_co_u32_e32 v81, vcc, 0, v105, vcc
	global_load_dwordx4 v[76:79], v[76:77], off
	v_add_co_u32_e32 v84, vcc, s30, v104
	global_load_dwordx4 v[80:83], v[80:81], off
	s_nop 0
	v_addc_co_u32_e32 v85, vcc, 0, v105, vcc
	global_load_dwordx4 v[84:87], v[84:85], off
	v_or_b32_e32 v100, 5, v108
	global_load_dwordx4 v[88:91], v66, s[48:49] offset:16
	global_load_dwordx4 v[92:95], v66, s[46:47] offset:16
	v_ashrrev_i32_e32 v101, 31, v100
	v_lshl_add_u64 v[96:97], v[104:105], 0, s[16:17]
	global_load_dwordx4 v[96:99], v[96:97], off offset:16
	v_lshlrev_b64 v[106:107], 13, v[100:101]
	v_lshl_add_u64 v[100:101], v[104:105], 0, s[18:19]
	global_load_dwordx4 v[100:103], v[100:101], off offset:16
	v_lshl_add_u64 v[104:105], v[104:105], 0, s[20:21]
	v_lshl_add_u64 v[122:123], v[110:111], 0, v[106:107]
	global_load_dwordx4 v[104:107], v[104:105], off offset:16
	v_or_b32_e32 v212, 6, v108
	v_ashrrev_i32_e32 v213, 31, v212
	v_or_b32_e32 v214, 7, v108
	v_lshlrev_b64 v[212:213], 13, v[212:213]
	v_ashrrev_i32_e32 v215, 31, v214
	v_lshl_add_u64 v[212:213], v[110:111], 0, v[212:213]
	v_lshlrev_b64 v[214:215], 13, v[214:215]
	v_lshl_add_u64 v[214:215], v[110:111], 0, v[214:215]
	global_load_ushort v227, v[112:113], off
	global_load_ushort v226, v[114:115], off
	global_load_ushort v225, v[116:117], off
	global_load_ushort v224, v[118:119], off
	global_load_ushort v223, v[120:121], off
	global_load_ushort v222, v[122:123], off
	global_load_ushort v221, v[212:213], off
	global_load_ushort v219, v[214:215], off
	v_or_b32_e32 v112, 8, v108
	v_or_b32_e32 v212, 14, v108
	v_ashrrev_i32_e32 v113, 31, v112
	v_or_b32_e32 v114, 9, v108
	v_or_b32_e32 v116, 10, v108
	v_or_b32_e32 v118, 11, v108
	v_or_b32_e32 v120, 12, v108
	v_or_b32_e32 v122, 13, v108
	v_ashrrev_i32_e32 v213, 31, v212
	v_or_b32_e32 v108, 15, v108
	v_lshlrev_b64 v[112:113], 13, v[112:113]
	v_ashrrev_i32_e32 v115, 31, v114
	v_ashrrev_i32_e32 v117, 31, v116
	v_ashrrev_i32_e32 v119, 31, v118
	v_ashrrev_i32_e32 v121, 31, v120
	v_ashrrev_i32_e32 v123, 31, v122
	v_lshlrev_b64 v[212:213], 13, v[212:213]
	v_ashrrev_i32_e32 v109, 31, v108
	v_lshl_add_u64 v[112:113], v[110:111], 0, v[112:113]
	v_lshlrev_b64 v[114:115], 13, v[114:115]
	v_lshlrev_b64 v[116:117], 13, v[116:117]
	v_lshlrev_b64 v[118:119], 13, v[118:119]
	v_lshlrev_b64 v[120:121], 13, v[120:121]
	v_lshlrev_b64 v[122:123], 13, v[122:123]
	v_lshl_add_u64 v[212:213], v[110:111], 0, v[212:213]
	v_lshlrev_b64 v[108:109], 13, v[108:109]
	v_lshl_add_u64 v[114:115], v[110:111], 0, v[114:115]
	v_lshl_add_u64 v[116:117], v[110:111], 0, v[116:117]
	v_lshl_add_u64 v[118:119], v[110:111], 0, v[118:119]
	v_lshl_add_u64 v[120:121], v[110:111], 0, v[120:121]
	v_lshl_add_u64 v[122:123], v[110:111], 0, v[122:123]
	v_lshl_add_u64 v[108:109], v[110:111], 0, v[108:109]
	global_load_ushort v220, v[112:113], off
	global_load_ushort v218, v[114:115], off
	global_load_ushort v217, v[116:117], off
	global_load_ushort v216, v[118:119], off
	global_load_ushort v215, v[120:121], off
	global_load_ushort v214, v[122:123], off
	s_nop 0
	global_load_ushort v213, v[212:213], off
	s_nop 0
	global_load_ushort v212, v[108:109], off
	s_waitcnt vmcnt(16)
; __device__ __forceinline__ void unpack8(u32x4 w, float* f) { f[0] = bflo(w.x); f[1] = bfhi(w.x); f[2] = bflo(w.y); f[3] = bfhi(w.y); f[4] = bflo(w.z); f[5] = bfhi(w.z); f[6] = bflo(w.w); f[7] = bfhi(w.w); }
; template <int PASS> __device__ void lru_phase(const Params& p, unsigned char* smem) {
;     ...
;         for (int it = 0; it < 2; ++it) {
;             const int t = (tid >> 4) + 32 * it, c8 = (tid & 15) * 8, ch = jb * 128 + c8;
;             float acc[8];
;             { const f32x4 b0 = *(const f32x4*)(cb + ch), b1 = *(const f32x4*)(cb + ch + 4);
; #pragma unroll
;               for (int i = 0; i < 4; ++i) { acc[i] = b0[i]; acc[4 + i] = b1[i]; } }
; #pragma unroll
;             for (int j = 0; j < 4; ++j) { float xv[8]; unpack8(craw[it][j], xv);
;                 const f32x4 w0 = *(const f32x4*)(cw + j * 2048 + ch), w1 = *(const f32x4*)(cw + j * 2048 + ch + 4);
; #pragma unroll
;                 for (int i = 0; i < 4; ++i) { acc[i] += w0[i] * xv[i]; acc[4 + i] += w1[i] * xv[4 + i]; } }
;             *(f32x4*)(xcf + t * 132 + c8) = (f32x4){acc[0], acc[1], acc[2], acc[3]}; *(f32x4*)(xcf + t * 132 + c8 + 4) = (f32x4){acc[4], acc[5], acc[6], acc[7]};
;         }
;         if (tile + (int)gridDim.x < 4096) LRU_CLOAD(tile + (int)gridDim.x);
	v_lshlrev_b32_e32 v108, 16, v6
	v_and_b32_e32 v109, 0xffff0000, v6
	v_lshlrev_b32_e32 v110, 16, v2
	v_and_b32_e32 v111, 0xffff0000, v2
	v_lshlrev_b32_e32 v112, 16, v4
	v_and_b32_e32 v113, 0xffff0000, v4
	v_lshlrev_b32_e32 v114, 16, v3
	v_and_b32_e32 v115, 0xffff0000, v3
	v_lshlrev_b32_e32 v116, 16, v5
	v_and_b32_e32 v117, 0xffff0000, v5
	s_add_i32 s37, s37, s62
	s_cmpk_gt_i32 s37, 0xfff
	s_cselect_b64 s[22:23], -1, 0
	s_and_b64 vcc, exec, s[22:23]
	v_readlane_b32 s45, v251, 1
	v_readlane_b32 s50, v251, 6
	v_readlane_b32 s51, v251, 7
	v_pk_fma_f32 v[108:109], v[72:73], v[108:109], v[68:69]
	v_readlane_b32 s52, v251, 8
	v_readlane_b32 s53, v251, 9
	v_pk_fma_f32 v[108:109], v[76:77], v[110:111], v[108:109]
	v_lshlrev_b32_e32 v110, 16, v10
	v_and_b32_e32 v111, 0xffff0000, v10
	v_pk_fma_f32 v[108:109], v[80:81], v[110:111], v[108:109]
	v_lshlrev_b32_e32 v110, 16, v14
	v_and_b32_e32 v111, 0xffff0000, v14
	v_pk_fma_f32 v[108:109], v[84:85], v[110:111], v[108:109]
	v_lshlrev_b32_e32 v110, 16, v8
	v_and_b32_e32 v111, 0xffff0000, v8
	v_pk_fma_f32 v[110:111], v[92:93], v[110:111], v[88:89]
	v_readlane_b32 s54, v251, 10
	v_pk_fma_f32 v[110:111], v[96:97], v[112:113], v[110:111]
	v_lshlrev_b32_e32 v112, 16, v12
	v_and_b32_e32 v113, 0xffff0000, v12
	v_pk_fma_f32 v[110:111], v[100:101], v[112:113], v[110:111]
	v_lshlrev_b32_e32 v112, 16, v16
	v_and_b32_e32 v113, 0xffff0000, v16
	v_pk_fma_f32 v[112:113], v[104:105], v[112:113], v[110:111]
	v_lshlrev_b32_e32 v110, 16, v7
	v_and_b32_e32 v111, 0xffff0000, v7
	v_pk_fma_f32 v[110:111], v[74:75], v[110:111], v[70:71]
	v_readlane_b32 s55, v251, 11
	v_pk_fma_f32 v[110:111], v[78:79], v[114:115], v[110:111]
	v_lshlrev_b32_e32 v114, 16, v11
	v_and_b32_e32 v115, 0xffff0000, v11
	v_pk_fma_f32 v[110:111], v[82:83], v[114:115], v[110:111]
	v_lshlrev_b32_e32 v114, 16, v15
	v_and_b32_e32 v115, 0xffff0000, v15
	v_pk_fma_f32 v[110:111], v[86:87], v[114:115], v[110:111]
	v_lshlrev_b32_e32 v114, 16, v9
	v_and_b32_e32 v115, 0xffff0000, v9
	v_pk_fma_f32 v[114:115], v[94:95], v[114:115], v[90:91]
	v_readlane_b32 s56, v251, 12
	v_pk_fma_f32 v[114:115], v[98:99], v[116:117], v[114:115]
	v_lshlrev_b32_e32 v116, 16, v13
	v_and_b32_e32 v117, 0xffff0000, v13
	v_pk_fma_f32 v[114:115], v[102:103], v[116:117], v[114:115]
	v_lshlrev_b32_e32 v116, 16, v17
	v_and_b32_e32 v117, 0xffff0000, v17
	v_pk_fma_f32 v[114:115], v[106:107], v[116:117], v[114:115]
	ds_write_b128 v206, v[108:111]
	ds_write_b128 v206, v[112:115] offset:16
	v_lshlrev_b32_e32 v108, 16, v18
	v_and_b32_e32 v109, 0xffff0000, v18
	v_pk_fma_f32 v[68:69], v[72:73], v[108:109], v[68:69]
	v_lshlrev_b32_e32 v72, 16, v22
	v_and_b32_e32 v73, 0xffff0000, v22
	v_pk_fma_f32 v[68:69], v[76:77], v[72:73], v[68:69]
	v_lshlrev_b32_e32 v72, 16, v26
	v_and_b32_e32 v73, 0xffff0000, v26
	v_pk_fma_f32 v[68:69], v[80:81], v[72:73], v[68:69]
	v_lshlrev_b32_e32 v72, 16, v30
	v_and_b32_e32 v73, 0xffff0000, v30
	v_pk_fma_f32 v[68:69], v[84:85], v[72:73], v[68:69]
	v_lshlrev_b32_e32 v72, 16, v20
	v_and_b32_e32 v73, 0xffff0000, v20
	v_pk_fma_f32 v[72:73], v[92:93], v[72:73], v[88:89]
	v_lshlrev_b32_e32 v76, 16, v24
	v_and_b32_e32 v77, 0xffff0000, v24
	v_pk_fma_f32 v[72:73], v[96:97], v[76:77], v[72:73]
	v_lshlrev_b32_e32 v76, 16, v28
	v_and_b32_e32 v77, 0xffff0000, v28
	v_pk_fma_f32 v[72:73], v[100:101], v[76:77], v[72:73]
	v_lshlrev_b32_e32 v76, 16, v32
	v_and_b32_e32 v77, 0xffff0000, v32
	v_pk_fma_f32 v[72:73], v[104:105], v[76:77], v[72:73]
	v_lshlrev_b32_e32 v76, 16, v19
	v_and_b32_e32 v77, 0xffff0000, v19
	v_pk_fma_f32 v[70:71], v[74:75], v[76:77], v[70:71]
	v_lshlrev_b32_e32 v74, 16, v23
	v_and_b32_e32 v75, 0xffff0000, v23
	v_pk_fma_f32 v[70:71], v[78:79], v[74:75], v[70:71]
	v_lshlrev_b32_e32 v74, 16, v27
	v_and_b32_e32 v75, 0xffff0000, v27
	v_pk_fma_f32 v[70:71], v[82:83], v[74:75], v[70:71]
	v_lshlrev_b32_e32 v74, 16, v31
	v_and_b32_e32 v75, 0xffff0000, v31
	v_pk_fma_f32 v[70:71], v[86:87], v[74:75], v[70:71]
	v_lshlrev_b32_e32 v74, 16, v21
	v_and_b32_e32 v75, 0xffff0000, v21
	v_pk_fma_f32 v[74:75], v[94:95], v[74:75], v[90:91]
	v_lshlrev_b32_e32 v76, 16, v25
	v_and_b32_e32 v77, 0xffff0000, v25
	v_pk_fma_f32 v[74:75], v[98:99], v[76:77], v[74:75]
	v_lshlrev_b32_e32 v76, 16, v29
	v_and_b32_e32 v77, 0xffff0000, v29
	v_pk_fma_f32 v[74:75], v[102:103], v[76:77], v[74:75]
	v_lshlrev_b32_e32 v76, 16, v33
	v_and_b32_e32 v77, 0xffff0000, v33
	v_readlane_b32 s57, v251, 13
	v_readlane_b32 s58, v251, 14
	v_readlane_b32 s59, v251, 15
	v_pk_fma_f32 v[74:75], v[106:107], v[76:77], v[74:75]
	ds_write_b128 v206, v[68:71] offset:16896
	ds_write_b128 v206, v[72:75] offset:16912
	s_cbranch_vccnz .LBB0_552
	s_lshl_b32 s4, s37, 7
	s_and_b32 s4, s4, 0x780
	v_or_b32_e32 v2, s4, v134
	s_lshl_b32 s4, s37, 2
	s_and_b32 s12, s4, 0xfc0
	v_mov_b32_e32 v4, v67
	v_mov_b32_e32 v5, v67
	v_add_u32_e32 v14, s12, v135
	v_lshlrev_b32_e32 v66, 1, v2
	v_mov_b32_e32 v2, v67
	v_mov_b32_e32 v3, v67
	v_mov_b64_e32 v[8:9], v[4:5]
	s_and_b32 s41, s4, 0xfffff000
	v_lshl_add_u64 v[30:31], s[0:1], 0, v[66:67]
	v_cmp_lt_i32_e32 vcc, -1, v14
	v_mov_b64_e32 v[6:7], v[2:3]
	s_and_saveexec_b64 s[4:5], vcc
	s_cbranch_execz .LBB0_545
	v_add_u32_e32 v6, s41, v14
	v_ashrrev_i32_e32 v7, 31, v6
	v_lshlrev_b64 v[6:7], 12, v[6:7]
	v_lshl_add_u64 v[6:7], v[30:31], 0, v[6:7]
	global_load_dwordx4 v[6:9], v[6:7], off

; __device__ __forceinline__ float softplusf_(float x) { return fmaxf(x, 0.f) + log1pf(__expf(-fabsf(x))); }
; __device__ __forceinline__ float fsig0(float x) { return __builtin_amdgcn_rcpf(1.0f + __expf(-x)); }
; template <int PASS> __device__ void lru_phase(const Params& p, unsigned char* smem) {
;     ...
;         {
;             const int ch = 16 * wave + (lane & 15), cgl = jb * 128 + ch;
;             const float ba_ = jb_fixed ? hb_a : p.in[6][cgl], bx_ = jb_fixed ? hb_x : p.in[8][cgl], sp = jb_fixed ? hsp : softplusf_(-p.in[9][cgl]);
; #pragma unroll
;             for (int m = 0; m < 4; ++m)
; #pragma unroll
;                 for (int r = 0; r < 4; ++r) { const int t = 16 * m + 4 * (lane >> 4) + r;
;                     const float rg = fsig0(accA[m][r] + ba_), ig = fsig0(accX[m][r] + bx_);
;                     const float la = -8.0f * rg * sp, a = __expf(la), u = __builtin_amdgcn_sqrtf(fmaxf(1.0f - a * a, 0.f)) * (ig * xcf[t * 132 + ch]);
;                     As[t * 132 + ch] = a; Us[t * 132 + ch] = u; }
;         }
.LBB0_572:
	s_waitcnt vmcnt(0)
	v_add_f32_e32 v66, v96, v100
	v_add_f32_e32 v96, v97, v100
	v_mul_f32_e32 v96, 0xbfb8aa3b, v96
	v_exp_f32_e32 v96, v96
	v_mul_f32_e32 v66, 0xbfb8aa3b, v66
	v_exp_f32_e32 v66, v66
	v_add_f32_e32 v93, v93, v101
	v_add_f32_e32 v96, 1.0, v96
	v_rcp_f32_e32 v96, v96
	v_add_f32_e32 v66, 1.0, v66
	v_mul_f32_e32 v93, 0xbfb8aa3b, v93
	v_rcp_f32_e32 v66, v66
	v_mul_f32_e32 v96, 0xc1000000, v96
	v_mul_f32_e32 v96, v96, v102
	v_mul_f32_e32 v96, 0x3fb8aa3b, v96
	v_exp_f32_e32 v93, v93
	v_exp_f32_e32 v96, v96
	ds_read2_b32 v[104:105], v141 offset1:132
	v_mul_f32_e32 v66, 0xc1000000, v66
	v_add_f32_e32 v93, 1.0, v93
	v_fma_f32 v103, -v96, v96, 1.0
	v_mul_f32_e32 v66, v66, v102
	v_rcp_f32_e32 v93, v93
	v_max_f32_e32 v103, 0, v103
	v_add_f32_e32 v98, v98, v100
	v_mul_f32_e32 v66, 0x3fb8aa3b, v66
	v_sqrt_f32_e32 v103, v103
	v_mul_f32_e32 v98, 0xbfb8aa3b, v98
	v_exp_f32_e32 v66, v66
	v_exp_f32_e32 v98, v98
	s_waitcnt lgkmcnt(0)
	v_mul_f32_e32 v93, v93, v105
	v_mul_f32_e32 v93, v93, v103
	v_add_u32_e32 v103, 0x8400, v141
	v_fma_f32 v97, -v66, v66, 1.0
	ds_write2_b32 v103, v66, v96 offset1:132
	v_add_f32_e32 v66, 1.0, v98
	v_rcp_f32_e32 v66, v66
	v_add_f32_e32 v94, v94, v101
	v_add_f32_e32 v98, v99, v100
	v_mul_f32_e32 v94, 0xbfb8aa3b, v94
	v_mul_f32_e32 v66, 0xc1000000, v66
	v_mul_f32_e32 v66, v66, v102
	v_mul_f32_e32 v66, 0x3fb8aa3b, v66
	v_mul_f32_e32 v98, 0xbfb8aa3b, v98
	v_exp_f32_e32 v94, v94
	v_exp_f32_e32 v66, v66
	v_exp_f32_e32 v98, v98
	ds_write_b32 v143, v93
	v_add_f32_e32 v93, 1.0, v94
	v_fma_f32 v94, -v66, v66, 1.0
	ds_read_b32 v96, v141 offset:1056
	ds_write_b32 v141, v66 offset:34848
	v_add_f32_e32 v66, 1.0, v98
	v_rcp_f32_e32 v93, v93
	v_max_f32_e32 v94, 0, v94
	v_rcp_f32_e32 v66, v66
	v_sqrt_f32_e32 v94, v94
	s_waitcnt lgkmcnt(1)
	v_mul_f32_e32 v93, v93, v96
	v_add_f32_e32 v88, v88, v100
	v_mul_f32_e32 v66, 0xc1000000, v66
	v_mul_f32_e32 v93, v94, v93
	v_add_f32_e32 v94, v95, v101
	v_mul_f32_e32 v66, v66, v102
	v_mul_f32_e32 v94, 0xbfb8aa3b, v94
	v_mul_f32_e32 v66, 0x3fb8aa3b, v66
	v_mul_f32_e32 v88, 0xbfb8aa3b, v88
	v_exp_f32_e32 v94, v94
	v_exp_f32_e32 v66, v66
	v_exp_f32_e32 v88, v88
	ds_write_b32 v144, v93
	v_add_f32_e32 v93, 1.0, v94
	v_fma_f32 v94, -v66, v66, 1.0
	ds_write_b32 v141, v66 offset:35376
	v_add_f32_e32 v66, 1.0, v88
	v_rcp_f32_e32 v66, v66
	ds_read_b32 v95, v141 offset:1584
	v_rcp_f32_e32 v93, v93
	v_max_f32_e32 v94, 0, v94
	v_mul_f32_e32 v66, 0xc1000000, v66
	v_mul_f32_e32 v66, v66, v102
	v_add_f32_e32 v89, v89, v100
	v_sqrt_f32_e32 v94, v94
	v_mul_f32_e32 v66, 0x3fb8aa3b, v66
	v_mul_f32_e32 v89, 0xbfb8aa3b, v89
	v_exp_f32_e32 v66, v66
	v_exp_f32_e32 v89, v89
	s_waitcnt lgkmcnt(0)
	v_mul_f32_e32 v93, v93, v95
	v_add_f32_e32 v84, v84, v101
	v_mul_f32_e32 v93, v94, v93
	v_mul_f32_e32 v84, 0xbfb8aa3b, v84
	v_exp_f32_e32 v84, v84
	ds_write_b32 v145, v93
	v_fma_f32 v88, -v66, v66, 1.0
	ds_write_b32 v141, v66 offset:42240
	v_add_f32_e32 v66, 1.0, v89
	v_rcp_f32_e32 v66, v66
	v_add_f32_e32 v84, 1.0, v84
	ds_read_b32 v93, v141 offset:8448
	v_rcp_f32_e32 v84, v84
	v_max_f32_e32 v88, 0, v88
	v_mul_f32_e32 v66, 0xc1000000, v66
	v_sqrt_f32_e32 v88, v88
	v_add_f32_e32 v85, v85, v101
	v_mul_f32_e32 v66, v66, v102
	v_add_f32_e32 v89, v90, v100
	v_mul_f32_e32 v85, 0xbfb8aa3b, v85
	v_mul_f32_e32 v66, 0x3fb8aa3b, v66
	v_mul_f32_e32 v89, 0xbfb8aa3b, v89
	v_exp_f32_e32 v85, v85
	v_exp_f32_e32 v66, v66
	v_exp_f32_e32 v89, v89
	s_waitcnt lgkmcnt(0)
	v_mul_f32_e32 v84, v84, v93
	v_mul_f32_e32 v84, v88, v84
	ds_write_b32 v146, v84
	v_add_f32_e32 v84, 1.0, v85
	v_fma_f32 v85, -v66, v66, 1.0
	ds_read_b32 v88, v141 offset:8976
	ds_write_b32 v141, v66 offset:42768
	v_add_f32_e32 v66, 1.0, v89
	v_rcp_f32_e32 v84, v84
	v_max_f32_e32 v85, 0, v85
	v_rcp_f32_e32 v66, v66
	v_sqrt_f32_e32 v85, v85
	s_waitcnt lgkmcnt(1)
	v_mul_f32_e32 v84, v84, v88
	v_add_f32_e32 v88, v91, v100
	v_mul_f32_e32 v66, 0xc1000000, v66
	v_mul_f32_e32 v84, v85, v84
	v_add_f32_e32 v85, v86, v101
	v_mul_f32_e32 v66, v66, v102
	v_mul_f32_e32 v85, 0xbfb8aa3b, v85
	v_mul_f32_e32 v66, 0x3fb8aa3b, v66
	v_mul_f32_e32 v88, 0xbfb8aa3b, v88
	v_exp_f32_e32 v85, v85
	v_exp_f32_e32 v66, v66
	v_exp_f32_e32 v88, v88
	ds_write_b32 v147, v84
	v_add_f32_e32 v84, 1.0, v85
	v_fma_f32 v85, -v66, v66, 1.0
	ds_read_b32 v86, v141 offset:9504
	ds_write_b32 v141, v66 offset:43296
	v_add_f32_e32 v66, 1.0, v88
	v_rcp_f32_e32 v84, v84
	v_max_f32_e32 v85, 0, v85
	v_rcp_f32_e32 v66, v66
	v_sqrt_f32_e32 v85, v85
	s_waitcnt lgkmcnt(1)
	v_mul_f32_e32 v84, v84, v86
	v_add_f32_e32 v80, v80, v100
	v_mul_f32_e32 v66, 0xc1000000, v66
	v_mul_f32_e32 v84, v85, v84
	v_add_f32_e32 v85, v87, v101
	v_mul_f32_e32 v66, v66, v102
	v_mul_f32_e32 v85, 0xbfb8aa3b, v85
	v_mul_f32_e32 v66, 0x3fb8aa3b, v66
	v_mul_f32_e32 v80, 0xbfb8aa3b, v80
	v_exp_f32_e32 v85, v85
	v_exp_f32_e32 v66, v66
	v_exp_f32_e32 v80, v80
	ds_write_b32 v148, v84
	v_add_f32_e32 v84, 1.0, v85
	v_fma_f32 v85, -v66, v66, 1.0
	ds_write_b32 v141, v66 offset:43824
	v_add_f32_e32 v66, 1.0, v80
	v_rcp_f32_e32 v66, v66
	ds_read_b32 v86, v141 offset:10032
	v_rcp_f32_e32 v84, v84
	v_max_f32_e32 v85, 0, v85
	v_mul_f32_e32 v66, 0xc1000000, v66
	v_mul_f32_e32 v66, v66, v102
	v_add_f32_e32 v81, v81, v100
	v_sqrt_f32_e32 v85, v85
	v_mul_f32_e32 v66, 0x3fb8aa3b, v66
	v_mul_f32_e32 v81, 0xbfb8aa3b, v81
	v_exp_f32_e32 v66, v66
	v_exp_f32_e32 v81, v81
	s_waitcnt lgkmcnt(0)
; __device__ __forceinline__ float softplusf_(float x) { return fmaxf(x, 0.f) + log1pf(__expf(-fabsf(x))); }
; #define LBAR0() do { asm volatile("s_waitcnt lgkmcnt(0)" ::: "memory"); __builtin_amdgcn_s_barrier(); asm volatile("" ::: "memory"); } while (0)
; __device__ __forceinline__ float fsig0(float x) { return __builtin_amdgcn_rcpf(1.0f + __expf(-x)); }
; template <int PASS> __device__ void lru_phase(const Params& p, unsigned char* smem) {
;     ...
;         {
;             const int ch = 16 * wave + (lane & 15), cgl = jb * 128 + ch;
;             const float ba_ = jb_fixed ? hb_a : p.in[6][cgl], bx_ = jb_fixed ? hb_x : p.in[8][cgl], sp = jb_fixed ? hsp : softplusf_(-p.in[9][cgl]);
; #pragma unroll
;             for (int m = 0; m < 4; ++m)
; #pragma unroll
;                 for (int r = 0; r < 4; ++r) { const int t = 16 * m + 4 * (lane >> 4) + r;
;                     const float rg = fsig0(accA[m][r] + ba_), ig = fsig0(accX[m][r] + bx_);
;                     const float la = -8.0f * rg * sp, a = __expf(la), u = __builtin_amdgcn_sqrtf(fmaxf(1.0f - a * a, 0.f)) * (ig * xcf[t * 132 + ch]);
;                     As[t * 132 + ch] = a; Us[t * 132 + ch] = u; }
;         }
;         LBAR0();
	v_mul_f32_e32 v84, v84, v86
	v_add_f32_e32 v76, v76, v101
	v_mul_f32_e32 v84, v85, v84
	v_mul_f32_e32 v76, 0xbfb8aa3b, v76
	v_exp_f32_e32 v76, v76
	ds_write_b32 v149, v84
	v_fma_f32 v80, -v66, v66, 1.0
	ds_write_b32 v141, v66 offset:50688
	v_add_f32_e32 v66, 1.0, v81
	v_rcp_f32_e32 v66, v66
	v_add_f32_e32 v76, 1.0, v76
	ds_read_b32 v84, v141 offset:16896
	v_rcp_f32_e32 v76, v76
	v_max_f32_e32 v80, 0, v80
	v_mul_f32_e32 v66, 0xc1000000, v66
	v_sqrt_f32_e32 v80, v80
	v_add_f32_e32 v77, v77, v101
	v_mul_f32_e32 v66, v66, v102
	v_add_f32_e32 v81, v82, v100
	v_mul_f32_e32 v77, 0xbfb8aa3b, v77
	v_mul_f32_e32 v66, 0x3fb8aa3b, v66
	v_mul_f32_e32 v81, 0xbfb8aa3b, v81
	v_exp_f32_e32 v77, v77
	v_exp_f32_e32 v66, v66
	v_exp_f32_e32 v81, v81
	s_waitcnt lgkmcnt(0)
	v_mul_f32_e32 v76, v76, v84
	v_mul_f32_e32 v76, v80, v76
	ds_write_b32 v150, v76
	v_add_f32_e32 v76, 1.0, v77
	v_fma_f32 v77, -v66, v66, 1.0
	ds_read_b32 v80, v141 offset:17424
	ds_write_b32 v141, v66 offset:51216
	v_add_f32_e32 v66, 1.0, v81
	v_rcp_f32_e32 v76, v76
	v_max_f32_e32 v77, 0, v77
	v_rcp_f32_e32 v66, v66
	v_sqrt_f32_e32 v77, v77
	s_waitcnt lgkmcnt(1)
	v_mul_f32_e32 v76, v76, v80
	v_add_f32_e32 v80, v83, v100
	v_mul_f32_e32 v66, 0xc1000000, v66
	v_mul_f32_e32 v76, v77, v76
	v_add_f32_e32 v77, v78, v101
	v_mul_f32_e32 v66, v66, v102
	v_mul_f32_e32 v77, 0xbfb8aa3b, v77
	v_mul_f32_e32 v66, 0x3fb8aa3b, v66
	v_mul_f32_e32 v80, 0xbfb8aa3b, v80
	v_exp_f32_e32 v77, v77
	v_exp_f32_e32 v66, v66
	v_exp_f32_e32 v80, v80
	ds_write_b32 v151, v76
	v_add_f32_e32 v76, 1.0, v77
	v_fma_f32 v77, -v66, v66, 1.0
	ds_read_b32 v78, v141 offset:17952
	ds_write_b32 v141, v66 offset:51744
	v_add_f32_e32 v66, 1.0, v80
	v_rcp_f32_e32 v76, v76
	v_max_f32_e32 v77, 0, v77
	v_rcp_f32_e32 v66, v66
	v_sqrt_f32_e32 v77, v77
	s_waitcnt lgkmcnt(1)
	v_mul_f32_e32 v76, v76, v78
	v_add_f32_e32 v72, v72, v100
	v_mul_f32_e32 v66, 0xc1000000, v66
	v_mul_f32_e32 v76, v77, v76
	v_add_f32_e32 v77, v79, v101
	v_mul_f32_e32 v66, v66, v102
	v_mul_f32_e32 v77, 0xbfb8aa3b, v77
	v_mul_f32_e32 v66, 0x3fb8aa3b, v66
	v_mul_f32_e32 v72, 0xbfb8aa3b, v72
	v_exp_f32_e32 v77, v77
	v_exp_f32_e32 v66, v66
	v_exp_f32_e32 v72, v72
	ds_write_b32 v152, v76
	v_add_f32_e32 v76, 1.0, v77
	v_fma_f32 v77, -v66, v66, 1.0
	ds_write_b32 v141, v66 offset:52272
	v_add_f32_e32 v66, 1.0, v72
	v_rcp_f32_e32 v66, v66
	ds_read_b32 v78, v141 offset:18480
	v_rcp_f32_e32 v76, v76
	v_max_f32_e32 v77, 0, v77
	v_mul_f32_e32 v66, 0xc1000000, v66
	v_mul_f32_e32 v66, v66, v102
	v_add_f32_e32 v73, v73, v100
	v_sqrt_f32_e32 v77, v77
	v_mul_f32_e32 v66, 0x3fb8aa3b, v66
	v_mul_f32_e32 v73, 0xbfb8aa3b, v73
	v_exp_f32_e32 v66, v66
	v_exp_f32_e32 v73, v73
	s_waitcnt lgkmcnt(0)
	v_mul_f32_e32 v76, v76, v78
	v_add_f32_e32 v68, v68, v101
	v_mul_f32_e32 v76, v77, v76
	v_mul_f32_e32 v68, 0xbfb8aa3b, v68
	v_exp_f32_e32 v68, v68
	ds_write_b32 v153, v76
	v_fma_f32 v72, -v66, v66, 1.0
	ds_write_b32 v141, v66 offset:59136
	v_add_f32_e32 v66, 1.0, v73
	v_rcp_f32_e32 v66, v66
	v_add_f32_e32 v68, 1.0, v68
	ds_read_b32 v76, v141 offset:25344
	v_rcp_f32_e32 v68, v68
	v_max_f32_e32 v72, 0, v72
	v_mul_f32_e32 v66, 0xc1000000, v66
	v_sqrt_f32_e32 v72, v72
	v_add_f32_e32 v69, v69, v101
	v_mul_f32_e32 v66, v66, v102
	v_add_f32_e32 v73, v74, v100
	v_mul_f32_e32 v69, 0xbfb8aa3b, v69
	v_mul_f32_e32 v66, 0x3fb8aa3b, v66
	v_mul_f32_e32 v73, 0xbfb8aa3b, v73
	v_exp_f32_e32 v69, v69
	v_exp_f32_e32 v66, v66
	v_exp_f32_e32 v73, v73
	s_waitcnt lgkmcnt(0)
	v_mul_f32_e32 v68, v68, v76
	v_mul_f32_e32 v68, v72, v68
	ds_write_b32 v154, v68
	v_add_f32_e32 v68, 1.0, v69
	v_fma_f32 v69, -v66, v66, 1.0
	ds_read_b32 v72, v141 offset:25872
	ds_write_b32 v141, v66 offset:59664
	v_add_f32_e32 v66, 1.0, v73
	v_rcp_f32_e32 v68, v68
	v_max_f32_e32 v69, 0, v69
	v_rcp_f32_e32 v66, v66
	v_sqrt_f32_e32 v69, v69
	s_waitcnt lgkmcnt(1)
	v_mul_f32_e32 v68, v68, v72
	v_add_f32_e32 v72, v75, v100
	v_mul_f32_e32 v66, 0xc1000000, v66
	v_mul_f32_e32 v68, v69, v68
	v_add_f32_e32 v69, v70, v101
	v_mul_f32_e32 v66, v66, v102
	v_mul_f32_e32 v69, 0xbfb8aa3b, v69
	v_mul_f32_e32 v66, 0x3fb8aa3b, v66
	v_mul_f32_e32 v72, 0xbfb8aa3b, v72
	v_exp_f32_e32 v69, v69
	v_exp_f32_e32 v66, v66
	v_exp_f32_e32 v72, v72
	ds_write_b32 v155, v68
	v_add_f32_e32 v68, 1.0, v69
	v_fma_f32 v69, -v66, v66, 1.0
	ds_read_b32 v70, v141 offset:26400
	ds_write_b32 v141, v66 offset:60192
	v_add_f32_e32 v66, 1.0, v72
	v_rcp_f32_e32 v68, v68
	v_max_f32_e32 v69, 0, v69
	v_rcp_f32_e32 v66, v66
	v_sqrt_f32_e32 v69, v69
	v_add_f32_e32 v92, v92, v101
	s_waitcnt lgkmcnt(1)
	v_mul_f32_e32 v68, v68, v70
	v_mul_f32_e32 v66, 0xc1000000, v66
	v_mul_f32_e32 v92, 0xbfb8aa3b, v92
	v_mul_f32_e32 v68, v69, v68
	v_add_f32_e32 v69, v71, v101
	v_mul_f32_e32 v66, v66, v102
	v_exp_f32_e32 v92, v92
	v_mul_f32_e32 v69, 0xbfb8aa3b, v69
	v_mul_f32_e32 v66, 0x3fb8aa3b, v66
	v_exp_f32_e32 v69, v69
	v_exp_f32_e32 v66, v66
	v_add_f32_e32 v92, 1.0, v92
	ds_write_b32 v156, v68
	v_rcp_f32_e32 v92, v92
	v_max_f32_e32 v97, 0, v97
	v_add_f32_e32 v68, 1.0, v69
	v_fma_f32 v69, -v66, v66, 1.0
	ds_read_b32 v70, v141 offset:26928
	v_sqrt_f32_e32 v97, v97
	v_rcp_f32_e32 v68, v68
	v_max_f32_e32 v69, 0, v69
	v_sqrt_f32_e32 v69, v69
	v_mul_f32_e32 v92, v92, v104
	v_mul_f32_e32 v71, v92, v97
	s_waitcnt lgkmcnt(0)
	v_mul_f32_e32 v68, v68, v70
	ds_write_b32 v142, v71
	v_mul_f32_e32 v68, v69, v68
	ds_write_b32 v141, v66 offset:60720
	ds_write_b32 v157, v68
	s_waitcnt lgkmcnt(0)
	s_barrier
; #define LBAR0() do { asm volatile("s_waitcnt lgkmcnt(0)" ::: "memory"); __builtin_amdgcn_s_barrier(); asm volatile("" ::: "memory"); } while (0)
; template <int PASS> __device__ void lru_phase(const Params& p, unsigned char* smem) {
;     ...
;         const int ch = tid & 127, q = tid >> 7, cgl = jb * 128 + ch;
;         { float h = 0.f, A = 1.f;
; #pragma unroll
;           for (int tt = 0; tt < 16; ++tt) { const int t = q * 16 + tt; const float a = As[t * 132 + ch], u = Us[t * 132 + ch]; h = a * h + u; A *= a;
;               if (PASS == 2) { Us[t * 132 + ch] = h; As[t * 132 + ch] = A; } }
;           qA[q * 128 + ch] = A; qH[q * 128 + ch] = h; }
;         LBAR0();
;         if (PASS == 1) {
;             if (q == 0) { float h = 0.f, A = 1.f;
; #pragma unroll
;                 for (int qq = 0; qq < 4; ++qq) { h = qA[qq * 128 + ch] * h + qH[qq * 128 + ch]; A *= qA[qq * 128 + ch]; }
;                 LA[(size_t)(b * 64 + c) * 2048 + cgl] = A; LH[(size_t)(b * 64 + c) * 2048 + cgl] = h; }
;         } else {
;             float carry = LC[(size_t)(b * 64 + c) * 2048 + cgl];
;             for (int qq = 0; qq < q; ++qq) carry = qA[qq * 128 + ch] * carry + qH[qq * 128 + ch];
	ds_read_b32 v72, v158 offset:33792
	ds_read_b32 v98, v1
	ds_read_b32 v73, v160 offset:33792
	ds_read_b32 v99, v161
	ds_read_b32 v74, v163 offset:33792
	ds_read_b32 v100, v164
	ds_read_b32 v75, v166 offset:33792
	ds_read_b32 v101, v167
	ds_read_b32 v76, v169 offset:33792
	ds_read_b32 v102, v170
	ds_read_b32 v77, v172 offset:33792
	ds_read_b32 v103, v173
	ds_read_b32 v78, v175 offset:33792
	ds_read_b32 v104, v176
	ds_read_b32 v79, v178 offset:33792
	ds_read_b32 v105, v179
	ds_read_b32 v80, v181 offset:33792
	ds_read_b32 v106, v182
	ds_read_b32 v81, v184 offset:33792
	ds_read_b32 v107, v185
	ds_read_b32 v82, v187 offset:33792
	ds_read_b32 v108, v188
	ds_read_b32 v83, v190 offset:33792
	ds_read_b32 v109, v191
	ds_read_b32 v84, v193 offset:33792
	ds_read_b32 v110, v194
	ds_read_b32 v85, v196 offset:33792
	ds_read_b32 v111, v197
	ds_read_b32 v86, v199 offset:33792
	ds_read_b32 v112, v200
	ds_read_b32 v87, v202 offset:33792
	ds_read_b32 v113, v203
	s_lshl_b32 s4, s25, 6
	s_or_b32 s4, s4, s24
	s_ashr_i32 s5, s4, 31
	s_lshl_b64 s[4:5], s[4:5], 13
	s_add_u32 s4, s26, s4
	s_addc_u32 s5, s27, s5
	v_or_b32_e32 v115, s39, v132
	v_lshlrev_b32_e32 v115, 2, v115
	global_load_dword v114, v115, s[4:5]
	s_waitcnt lgkmcnt(0)
	v_fmac_f32_e32 v98, 0, v72
	v_fmac_f32_e32 v99, v98, v73
	v_mul_f32_e32 v73, v72, v73
	v_fmac_f32_e32 v100, v99, v74
	v_mul_f32_e32 v74, v73, v74
	v_fmac_f32_e32 v101, v100, v75
	v_mul_f32_e32 v75, v74, v75
	v_fmac_f32_e32 v102, v101, v76
	v_mul_f32_e32 v76, v75, v76
	v_fmac_f32_e32 v103, v102, v77
	v_mul_f32_e32 v77, v76, v77
	v_fmac_f32_e32 v104, v103, v78
	v_mul_f32_e32 v78, v77, v78
	v_fmac_f32_e32 v105, v104, v79
	v_mul_f32_e32 v79, v78, v79
	v_fmac_f32_e32 v106, v105, v80
	v_mul_f32_e32 v80, v79, v80
	v_fmac_f32_e32 v107, v106, v81
	v_mul_f32_e32 v81, v80, v81
	v_fmac_f32_e32 v108, v107, v82
	v_mul_f32_e32 v82, v81, v82
	v_fmac_f32_e32 v109, v108, v83
	v_mul_f32_e32 v83, v82, v83
	v_fmac_f32_e32 v110, v109, v84
	v_mul_f32_e32 v84, v83, v84
	v_fmac_f32_e32 v111, v110, v85
	v_mul_f32_e32 v85, v84, v85
	v_fmac_f32_e32 v112, v111, v86
	v_mul_f32_e32 v86, v85, v86
	v_fmac_f32_e32 v113, v112, v87
	v_mul_f32_e32 v87, v86, v87
	ds_write_b32 v1, v98
	ds_write_b32 v161, v99
	ds_write_b32 v160, v73 offset:33792
	ds_write_b32 v164, v100
	ds_write_b32 v163, v74 offset:33792
	ds_write_b32 v167, v101
	ds_write_b32 v166, v75 offset:33792
	ds_write_b32 v170, v102
	ds_write_b32 v169, v76 offset:33792
	ds_write_b32 v173, v103
	ds_write_b32 v172, v77 offset:33792
	ds_write_b32 v176, v104
	ds_write_b32 v175, v78 offset:33792
	ds_write_b32 v179, v105
	ds_write_b32 v178, v79 offset:33792
	ds_write_b32 v182, v106
	ds_write_b32 v181, v80 offset:33792
	ds_write_b32 v185, v107
	ds_write_b32 v184, v81 offset:33792
	ds_write_b32 v188, v108
	ds_write_b32 v187, v82 offset:33792
	ds_write_b32 v191, v109
	ds_write_b32 v190, v83 offset:33792
	ds_write_b32 v194, v110
	ds_write_b32 v193, v84 offset:33792
	ds_write_b32 v197, v111
	ds_write_b32 v196, v85 offset:33792
	ds_write_b32 v200, v112
	ds_write_b32 v199, v86 offset:33792
	ds_write_b32 v203, v113
	v_mov_b32_e32 v70, v113
	v_mov_b32_e32 v68, v87
	ds_write_b32 v202, v68 offset:33792
	v_or_b32_e32 v66, s39, v132
	ds_write_b32 v139, v68
	ds_write_b32 v140, v70
	s_waitcnt lgkmcnt(0)
	s_barrier
	v_lshlrev_b32_e32 v68, 2, v66
	s_waitcnt vmcnt(0)
	v_mov_b32_e32 v70, v114
	s_and_saveexec_b64 s[4:5], s[2:3]
	s_cbranch_execz .LBB0_541
	s_mov_b64 s[24:25], 0
	v_mov_b32_e32 v68, v205
	v_mov_b32_e32 v69, v137
